# speedup vs baseline: 1.0401x; 1.0192x over previous
; DI int my_tid() { int t = threadIdx.x; asm volatile("" : "+v"(t)); return t; }
; #define PEER_SWAP() do { _Pragma("unroll") for (int q_ = 0; q_ < 8; ++q_) _Pragma("unroll") for (int c_ = 0; c_ < 4; ++c_) { \
;             const auto r_ = __builtin_amdgcn_permlane32_swap(ra[q_][c_], rb[q_][c_], false, false); ucur[q_][c_] = r_[0]; vcur[q_][c_] = r_[1]; } } while (0)
; #define PEER_LOADREC_MEM(ep_) do { \
;         _Pragma("unroll") for (int q_ = 0; q_ < 8; ++q_) { \
;             const int ia_ = __builtin_amdgcn_readfirstlane((ep_)[2 * q_]), ib_ = __builtin_amdgcn_readfirstlane((ep_)[2 * q_ + 1]); \
;             ra[q_] = *(const u32x4*)(REC + (size_t)ia_ * 1024); rb[q_] = *(const u32x4*)(REC + (size_t)ib_ * 1024); } } while (0)
; #define PEER_NEXTOPS(t_) do { const u32x4* xr_ = (const u32x4*)(xb + (size_t)(t_) * PA + 32 * l5); xq[0] = xr_[0]; xq[1] = xr_[1]; xq[2] = xr_[2]; xq[3] = xr_[3]; \
;         ivq0 = eidx[(size_t)(t_) * 128 + lane]; ivq1 = eidx[(size_t)(t_) * 128 + 64 + lane]; gvq0 = gate[(size_t)(t_) * 128 + lane]; gvq1 = gate[(size_t)(t_) * 128 + 64 + lane]; } while (0)
; DI void peer_phase(const Params& p, int layer, bool dry) {
;     unsigned char* ws = p.ws;
;     const int lane = my_tid() & 63, wid = __builtin_amdgcn_readfirstlane(my_tid() >> 6);
;     const int gw = blockIdx.x * NWV + wid, nw = gridDim.x * NWV;
;     const unsigned char* U6 = ws + OFF_U; const float* SU = (const float*)(ws + OFF_U + 16777216);
;     const unsigned char* V6 = ws + OFF_V; const float* SV = (const float*)(ws + OFF_V + 16777216);
;     bf16_t* xb = (bf16_t*)(ws + OFF_R2);
;     const float* x1f = (const float*)(ws + OFF_R3);
;     const int* eidx = (const int*)(ws + OFF_EIDX);
;     const float* gate = (const float*)(ws + OFF_GATE);
;     const float* g2 = p.in[16] + layer * DM;
;     const float* b2 = p.in[17] + layer * DM;
;     const int hi = lane >> 5, l5 = lane & 31, b4 = (lane >> 4) & 1, b3 = (lane >> 3) & 1, esel = 4 * b4 + 2 * b3 + hi;
;     u32x4 ucur[8], vcur[8], ra[8], rb[8];
;     const int b2_ = (lane >> 2) & 1, esel16 = 8 * b4 + 4 * b3 + 2 * b2_ + hi;
;     const unsigned char* REC = ws + OFF_U + 16 * lane;
;     ...
;     if (gw < T_TOK) {
;         PEER_LOADREC_MEM(eidx + (size_t)gw * 128);
;         PEER_SWAP();
;     }
;     u32x4 xq[4]; int ivq0 = 0, ivq1 = 0; float gvq0 = 0.f, gvq1 = 0.f;
;     ...
;     if (gw < T_TOK) PEER_NEXTOPS(gw);
.LBB0_28:
	v_readlane_b32 s0, v252, 34
	s_ashr_i32 s42, s0, 3
	s_and_b32 s28, s0, 7
	s_cmp_lt_u32 s0, 8
	v_readlane_b32 s1, v252, 35
	s_cselect_b64 s[2:3], -1, 0
	s_cmp_gt_u32 s0, 7
	v_writelane_b32 v250, s2, 21
	s_cselect_b64 s[12:13], -1, 0
	s_cmp_lt_i32 s28, 4
	s_mov_b64 s[0:1], -1
	v_writelane_b32 v250, s3, 22
	s_cbranch_scc1 .LBB0_130
	s_lshl_b32 s14, s42, 10
	s_ashr_i32 s15, s14, 31
	s_cmp_lt_i32 s28, 6
	s_cbranch_scc1 .LBB0_85
	s_cmp_gt_i32 s28, 6
	s_cbranch_scc0 .LBB0_51
	v_mov_b32_e32 v80, v192
	v_mov_b32_e32 v0, v192
	v_readlane_b32 s1, v252, 36
	v_readfirstlane_b32 s0, v0
	s_ashr_i32 s0, s0, 6
	s_mul_i32 s32, s0, 0x4100
	s_lshl_b32 s45, s0, 11
	s_add_i32 s45, s45, 0x20800
	v_writelane_b32 v250, s45, 42
	s_add_i32 s10, s0, s1
	s_mov_b32 s43, s28
	s_cmpk_gt_i32 s10, 0x7fff
	s_cbranch_scc1 .LBB0_50
	s_waitcnt vmcnt(0)
	v_and_b32_e32 v96, 63, v80
	v_readlane_b32 s0, v252, 37
	v_readlane_b32 s16, v250, 1
	v_lshlrev_b32_e32 v128, 4, v96
	v_lshlrev_b32_e32 v232, 4, v96
	v_lshrrev_b32_e32 v233, 5, v96
	v_mul_u32_u24_e32 v233, 0x410, v233
	v_and_b32_e32 v196, 31, v96
	v_readlane_b32 s12, v252, 37
	v_lshl_add_u32 v233, v196, 4, v233
	v_readlane_b32 s13, v252, 38
	v_add_u32_e32 v233, s32, v233
	v_and_b32_e32 v196, 15, v96
	v_mul_u32_u24_e32 v196, 0x410, v196
	v_lshrrev_b32_e32 v210, 4, v96
	v_lshl_add_u32 v196, v210, 4, v196
	v_add_u32_e32 v196, s32, v196
	v_lshlrev_b32_e32 v210, 6, v210
	v_add_u32_e32 v210, s45, v210
	v_readlane_b32 s1, v252, 38
	s_lshl_b64 s[2:3], s[14:15], 2
	v_readlane_b32 s18, v250, 3
	v_lshl_add_u64 v[98:99], s[0:1], 0, v[128:129]
	v_readlane_b32 s19, v250, 4
	s_add_u32 s0, s18, s2
	s_addc_u32 s1, s19, s3
	v_readlane_b32 s17, v250, 2
	s_add_u32 s18, s16, s2
	s_addc_u32 s19, s17, s3
	s_cmp_eq_u32 s42, 1
	s_cselect_b64 s[16:17], -1, 0
	s_ashr_i32 s11, s10, 31
	s_lshl_b64 s[2:3], s[10:11], 9
	v_bfe_u32 v85, v80, 4, 1
	v_bfe_u32 v84, v80, 3, 1
	v_bfe_u32 v83, v80, 2, 1
	s_add_u32 s4, s92, s2
	v_lshlrev_b32_e32 v0, 3, v85
	v_lshlrev_b32_e32 v1, 2, v84
	v_lshlrev_b32_e32 v2, 1, v83
	s_addc_u32 s5, s93, s3
	v_or3_b32 v81, v0, v1, v2
	v_lshlrev_b32_e32 v64, 5, v80
	v_and_b32_e32 v92, 0x3e0, v64
	v_lshl_or_b32 v86, v96, 2, s2
	v_mov_b32_e32 v87, s3
	v_lshlrev_b32_e32 v128, 1, v92
	v_lshl_add_u64 v[88:89], s[92:93], 0, v[86:87]
	v_cmp_lt_i32_e32 vcc, v199, v200
	v_bfe_u32 v82, v80, 5, 1
	v_lshl_add_u64 v[100:101], s[88:89], 0, v[128:129]
	v_and_or_b32 v80, v80, 32, v198
	v_readlane_b32 s20, v250, 5
	v_readlane_b32 s21, v250, 6
	v_lshrrev_b32_e32 v216, 3, v80
	v_cmp_gt_u32_e64 s[8:9], 32, v96
	v_or_b32_e32 v217, 8, v216
	v_or_b32_e32 v219, 16, v216
	v_or_b32_e32 v220, 24, v216
	v_or_b32_e32 v221, 32, v216
	v_or_b32_e32 v222, 40, v216
	v_or_b32_e32 v223, 48, v216
	v_or_b32_e32 v224, 56, v216
	v_readlane_b32 s22, v250, 7
	v_readlane_b32 s23, v250, 8
	global_load_dword v218, v[88:89], off
	v_or_b32_e32 v88, 0x100, v86
	v_mov_b32_e32 v89, s3
	v_lshl_add_u64 v[90:91], s[92:93], 0, v[88:89]
	v_lshl_add_u64 v[86:87], s[76:77], 0, v[86:87]
	global_load_dword v225, v[90:91], off
	global_load_dword v226, v[86:87], off
	v_lshl_add_u64 v[86:87], s[76:77], 0, v[88:89]
	global_load_dword v227, v[86:87], off
	s_waitcnt vmcnt(0)
	v_lshrrev_b32_e32 v64, 11, v218
	v_lshrrev_b32_e32 v65, 11, v225
	s_mov_b32 s36, 0
	v_cmp_eq_u32_e64 s[28:29], 0, v64
	v_cmp_eq_u32_e64 s[30:31], 0, v65
	s_bcnt1_i32_b64 s34, s[28:29]
	s_bcnt1_i32_b64 s35, s[30:31]
	v_mbcnt_lo_u32_b32 v68, s28, 0
	v_mbcnt_hi_u32_b32 v68, s29, v68
	v_mbcnt_lo_u32_b32 v69, s30, 0
	v_mbcnt_hi_u32_b32 v69, s31, v69
	v_add_u32_e32 v68, s36, v68
	s_add_i32 s36, s36, s34
	v_add_u32_e32 v69, s36, v69
	s_add_i32 s36, s36, s35
	v_cndmask_b32_e64 v66, v66, v68, s[28:29]
	v_cndmask_b32_e64 v67, v67, v69, s[30:31]
	v_cmp_eq_u32_e64 s[28:29], 1, v64
	v_cmp_eq_u32_e64 s[30:31], 1, v65
	s_bcnt1_i32_b64 s34, s[28:29]
	s_bcnt1_i32_b64 s35, s[30:31]
	v_mbcnt_lo_u32_b32 v68, s28, 0
	v_mbcnt_hi_u32_b32 v68, s29, v68
	v_mbcnt_lo_u32_b32 v69, s30, 0
	v_mbcnt_hi_u32_b32 v69, s31, v69
	v_add_u32_e32 v68, s36, v68
	s_add_i32 s36, s36, s34
	v_add_u32_e32 v69, s36, v69
	s_add_i32 s36, s36, s35
	v_cndmask_b32_e64 v66, v66, v68, s[28:29]
	v_cndmask_b32_e64 v67, v67, v69, s[30:31]
	v_cmp_eq_u32_e64 s[28:29], 2, v64
	v_cmp_eq_u32_e64 s[30:31], 2, v65
	s_bcnt1_i32_b64 s34, s[28:29]
	s_bcnt1_i32_b64 s35, s[30:31]
	v_mbcnt_lo_u32_b32 v68, s28, 0
	v_mbcnt_hi_u32_b32 v68, s29, v68
	v_mbcnt_lo_u32_b32 v69, s30, 0
	v_mbcnt_hi_u32_b32 v69, s31, v69
	v_add_u32_e32 v68, s36, v68
	s_add_i32 s36, s36, s34
	v_add_u32_e32 v69, s36, v69
	s_add_i32 s36, s36, s35
	v_cndmask_b32_e64 v66, v66, v68, s[28:29]
	v_cndmask_b32_e64 v67, v67, v69, s[30:31]
	v_cmp_eq_u32_e64 s[28:29], 3, v64
	v_cmp_eq_u32_e64 s[30:31], 3, v65
	s_bcnt1_i32_b64 s34, s[28:29]
	s_bcnt1_i32_b64 s35, s[30:31]
	v_mbcnt_lo_u32_b32 v68, s28, 0
	v_mbcnt_hi_u32_b32 v68, s29, v68
	v_mbcnt_lo_u32_b32 v69, s30, 0
	v_mbcnt_hi_u32_b32 v69, s31, v69
	v_add_u32_e32 v68, s36, v68
	s_add_i32 s36, s36, s34
	v_add_u32_e32 v69, s36, v69
	s_add_i32 s36, s36, s35
	v_cndmask_b32_e64 v66, v66, v68, s[28:29]
	v_cndmask_b32_e64 v67, v67, v69, s[30:31]
	v_cmp_eq_u32_e64 s[28:29], 4, v64
	v_cmp_eq_u32_e64 s[30:31], 4, v65
	s_bcnt1_i32_b64 s34, s[28:29]
	s_bcnt1_i32_b64 s35, s[30:31]
	v_mbcnt_lo_u32_b32 v68, s28, 0
	v_mbcnt_hi_u32_b32 v68, s29, v68
	v_mbcnt_lo_u32_b32 v69, s30, 0
	v_mbcnt_hi_u32_b32 v69, s31, v69
	v_add_u32_e32 v68, s36, v68
	s_add_i32 s36, s36, s34
	v_add_u32_e32 v69, s36, v69
	s_add_i32 s36, s36, s35
	v_cndmask_b32_e64 v66, v66, v68, s[28:29]
	v_cndmask_b32_e64 v67, v67, v69, s[30:31]
	v_cmp_eq_u32_e64 s[28:29], 5, v64
	v_cmp_eq_u32_e64 s[30:31], 5, v65
; #define PEER_SWAP() do { _Pragma("unroll") for (int q_ = 0; q_ < 8; ++q_) _Pragma("unroll") for (int c_ = 0; c_ < 4; ++c_) { \
;             const auto r_ = __builtin_amdgcn_permlane32_swap(ra[q_][c_], rb[q_][c_], false, false); ucur[q_][c_] = r_[0]; vcur[q_][c_] = r_[1]; } } while (0)
; #define PEER_LOADREC_MEM(ep_) do { \
;         _Pragma("unroll") for (int q_ = 0; q_ < 8; ++q_) { \
;             const int ia_ = __builtin_amdgcn_readfirstlane((ep_)[2 * q_]), ib_ = __builtin_amdgcn_readfirstlane((ep_)[2 * q_ + 1]); \
;             ra[q_] = *(const u32x4*)(REC + (size_t)ia_ * 1024); rb[q_] = *(const u32x4*)(REC + (size_t)ib_ * 1024); } } while (0)
; #define PEER_NEXTOPS(t_) do { const u32x4* xr_ = (const u32x4*)(xb + (size_t)(t_) * PA + 32 * l5); xq[0] = xr_[0]; xq[1] = xr_[1]; xq[2] = xr_[2]; xq[3] = xr_[3]; \
;         ivq0 = eidx[(size_t)(t_) * 128 + lane]; ivq1 = eidx[(size_t)(t_) * 128 + 64 + lane]; gvq0 = gate[(size_t)(t_) * 128 + lane]; gvq1 = gate[(size_t)(t_) * 128 + 64 + lane]; } while (0)
; DI void peer_phase(const Params& p, int layer, bool dry) {
;     ...
;     if (gw < T_TOK) {
;         PEER_LOADREC_MEM(eidx + (size_t)gw * 128);
;         PEER_SWAP();
;     }
;     u32x4 xq[4]; int ivq0 = 0, ivq1 = 0; float gvq0 = 0.f, gvq1 = 0.f;
;     ...
;     if (gw < T_TOK) PEER_NEXTOPS(gw);
	s_bcnt1_i32_b64 s34, s[28:29]
	s_bcnt1_i32_b64 s35, s[30:31]
	v_mbcnt_lo_u32_b32 v68, s28, 0
	v_mbcnt_hi_u32_b32 v68, s29, v68
	v_mbcnt_lo_u32_b32 v69, s30, 0
	v_mbcnt_hi_u32_b32 v69, s31, v69
	v_add_u32_e32 v68, s36, v68
	s_add_i32 s36, s36, s34
	v_add_u32_e32 v69, s36, v69
	s_add_i32 s36, s36, s35
	v_cndmask_b32_e64 v66, v66, v68, s[28:29]
	v_cndmask_b32_e64 v67, v67, v69, s[30:31]
	v_cmp_eq_u32_e64 s[28:29], 6, v64
	v_cmp_eq_u32_e64 s[30:31], 6, v65
	s_bcnt1_i32_b64 s34, s[28:29]
	s_bcnt1_i32_b64 s35, s[30:31]
	v_mbcnt_lo_u32_b32 v68, s28, 0
	v_mbcnt_hi_u32_b32 v68, s29, v68
	v_mbcnt_lo_u32_b32 v69, s30, 0
	v_mbcnt_hi_u32_b32 v69, s31, v69
	v_add_u32_e32 v68, s36, v68
	s_add_i32 s36, s36, s34
	v_add_u32_e32 v69, s36, v69
	s_add_i32 s36, s36, s35
	v_cndmask_b32_e64 v66, v66, v68, s[28:29]
	v_cndmask_b32_e64 v67, v67, v69, s[30:31]
	v_cmp_eq_u32_e64 s[28:29], 7, v64
	v_cmp_eq_u32_e64 s[30:31], 7, v65
	s_bcnt1_i32_b64 s34, s[28:29]
	s_bcnt1_i32_b64 s35, s[30:31]
	v_mbcnt_lo_u32_b32 v68, s28, 0
	v_mbcnt_hi_u32_b32 v68, s29, v68
	v_mbcnt_lo_u32_b32 v69, s30, 0
	v_mbcnt_hi_u32_b32 v69, s31, v69
	v_add_u32_e32 v68, s36, v68
	s_add_i32 s36, s36, s34
	v_add_u32_e32 v69, s36, v69
	s_add_i32 s36, s36, s35
	v_cndmask_b32_e64 v66, v66, v68, s[28:29]
	v_cndmask_b32_e64 v67, v67, v69, s[30:31]
	v_lshl_add_u32 v71, v66, 2, s32
	v_lshl_add_u32 v72, v67, 2, s32
	v_lshl_add_u32 v70, v96, 2, s32
	ds_write_b32 v71, v218
	ds_write_b32 v72, v225
	ds_write_b32 v71, v226 offset:512
	ds_write_b32 v72, v227 offset:512
	s_waitcnt lgkmcnt(0)
	ds_read_b32 v218, v70
	ds_read_b32 v225, v70 offset:256
	ds_read_b32 v226, v70 offset:512
	ds_read_b32 v227, v70 offset:768
	s_waitcnt lgkmcnt(0)
	v_readlane_b32 s44, v218, 0
	s_mov_b32 m0, s32
	s_lshl_b32 s44, s44, 10
	s_add_u32 s44, s12, s44
	s_addc_u32 s45, s13, 0
	global_load_lds_dwordx4 v232, s[44:45] sc1
	v_readlane_b32 s44, v218, 1
	s_add_i32 m0, s32, 0x410
	s_lshl_b32 s44, s44, 10
	s_add_u32 s44, s12, s44
	s_addc_u32 s45, s13, 0
	global_load_lds_dwordx4 v232, s[44:45] sc1
	v_readlane_b32 s44, v218, 2
	s_add_i32 m0, s32, 0x820
	s_lshl_b32 s44, s44, 10
	s_add_u32 s44, s12, s44
	s_addc_u32 s45, s13, 0
	global_load_lds_dwordx4 v232, s[44:45] sc1
	v_readlane_b32 s44, v218, 3
	s_add_i32 m0, s32, 0xc30
	s_lshl_b32 s44, s44, 10
	s_add_u32 s44, s12, s44
	s_addc_u32 s45, s13, 0
	global_load_lds_dwordx4 v232, s[44:45] sc1
	v_readlane_b32 s44, v218, 4
	s_add_i32 m0, s32, 0x1040
	s_lshl_b32 s44, s44, 10
	s_add_u32 s44, s12, s44
	s_addc_u32 s45, s13, 0
	global_load_lds_dwordx4 v232, s[44:45] sc1
	v_readlane_b32 s44, v218, 5
	s_add_i32 m0, s32, 0x1450
	s_lshl_b32 s44, s44, 10
	s_add_u32 s44, s12, s44
	s_addc_u32 s45, s13, 0
	global_load_lds_dwordx4 v232, s[44:45] sc1
	v_readlane_b32 s44, v218, 6
	s_add_i32 m0, s32, 0x1860
	s_lshl_b32 s44, s44, 10
	s_add_u32 s44, s12, s44
	s_addc_u32 s45, s13, 0
	global_load_lds_dwordx4 v232, s[44:45] sc1
	v_readlane_b32 s44, v218, 7
	s_add_i32 m0, s32, 0x1c70
	s_lshl_b32 s44, s44, 10
	s_add_u32 s44, s12, s44
	s_addc_u32 s45, s13, 0
	global_load_lds_dwordx4 v232, s[44:45] sc1
	v_readlane_b32 s44, v218, 8
	s_add_i32 m0, s32, 0x2080
	s_lshl_b32 s44, s44, 10
	s_add_u32 s44, s12, s44
	s_addc_u32 s45, s13, 0
	global_load_lds_dwordx4 v232, s[44:45] sc1
	v_readlane_b32 s44, v218, 9
	s_add_i32 m0, s32, 0x2490
	s_lshl_b32 s44, s44, 10
	s_add_u32 s44, s12, s44
	s_addc_u32 s45, s13, 0
	global_load_lds_dwordx4 v232, s[44:45] sc1
	v_readlane_b32 s44, v218, 10
	s_add_i32 m0, s32, 0x28a0
	s_lshl_b32 s44, s44, 10
	s_add_u32 s44, s12, s44
	s_addc_u32 s45, s13, 0
	global_load_lds_dwordx4 v232, s[44:45] sc1
	v_readlane_b32 s44, v218, 11
	s_add_i32 m0, s32, 0x2cb0
	s_lshl_b32 s44, s44, 10
	s_add_u32 s44, s12, s44
	s_addc_u32 s45, s13, 0
	global_load_lds_dwordx4 v232, s[44:45] sc1
	v_readlane_b32 s44, v218, 12
	s_add_i32 m0, s32, 0x30c0
	s_lshl_b32 s44, s44, 10
	s_add_u32 s44, s12, s44
	s_addc_u32 s45, s13, 0
	global_load_lds_dwordx4 v232, s[44:45] sc1
	v_readlane_b32 s44, v218, 13
	s_add_i32 m0, s32, 0x34d0
	s_lshl_b32 s44, s44, 10
	s_add_u32 s44, s12, s44
	s_addc_u32 s45, s13, 0
	global_load_lds_dwordx4 v232, s[44:45] sc1
	v_readlane_b32 s44, v218, 14
	s_add_i32 m0, s32, 0x38e0
	s_lshl_b32 s44, s44, 10
	s_add_u32 s44, s12, s44
	s_addc_u32 s45, s13, 0
	global_load_lds_dwordx4 v232, s[44:45] sc1
	v_readlane_b32 s44, v218, 15
	s_add_i32 m0, s32, 0x3cf0
	s_lshl_b32 s44, s44, 10
	s_add_u32 s44, s12, s44
	s_addc_u32 s45, s13, 0
	global_load_lds_dwordx4 v232, s[44:45] sc1
	s_lshl_b64 s[4:5], s[10:11], 11
	s_add_u32 s4, s88, s4
	s_addc_u32 s5, s89, s5
	global_load_dwordx4 v[64:67], v128, s[4:5] offset:48
	global_load_dwordx4 v[72:75], v128, s[4:5] offset:32
	global_load_dwordx4 v[68:71], v128, s[4:5] offset:16
	global_load_dwordx4 v[76:79], v128, s[4:5]
	v_cmp_eq_u32_e64 s[2:3], 0, v85
	v_cndmask_b32_e32 v85, v197, v199, vcc
	v_cmp_lt_i32_e32 vcc, v201, v200
	v_cmp_eq_u32_e64 s[4:5], 0, v84
	v_cmp_eq_u32_e64 s[6:7], 0, v83
	v_cndmask_b32_e32 v84, v197, v201, vcc
	v_cmp_lt_i32_e32 vcc, v202, v200
	v_lshlrev_b32_e32 v97, 2, v85
	v_lshlrev_b32_e32 v211, 2, v84
	v_cndmask_b32_e32 v83, v197, v202, vcc
	v_cmp_lt_i32_e32 vcc, v203, v200
	v_lshlrev_b32_e32 v212, 2, v83
	v_mov_b32_e32 v85, v129
	v_cndmask_b32_e32 v83, v197, v203, vcc
	v_cmp_lt_i32_e32 vcc, v204, v200
	v_lshlrev_b32_e32 v213, 2, v83
	v_cndmask_b32_e32 v83, v197, v204, vcc
	v_cmp_lt_i32_e32 vcc, v205, v200
	v_lshlrev_b32_e32 v214, 2, v83
	v_cndmask_b32_e32 v83, v197, v205, vcc
	v_lshlrev_b32_e32 v215, 2, v83
	v_lshl_or_b32 v83, v82, 4, v92
	v_lshlrev_b32_e32 v128, 2, v83
	v_lshl_add_u64 v[104:105], s[0:1], 0, v[128:129]
	v_readlane_b32 s0, v252, 39
	v_lshlrev_b32_e32 v84, 1, v83
	v_readlane_b32 s1, v252, 40
	v_lshl_add_u64 v[102:103], s[18:19], 0, v[128:129]
	v_lshl_add_u64 v[106:107], s[88:89], 0, v[84:85]
	v_lshl_add_u64 v[108:109], s[0:1], 0, v[84:85]
	v_lshl_add_u64 v[110:111], s[20:21], 0, v[128:129]
	v_and_b32_e32 v128, 15, v96
	s_waitcnt vmcnt(4)
; DI float bflo(unsigned w) { return __uint_as_float(w << 16); }
; DI float bfhi(unsigned w) { return __uint_as_float(w & 0xffff0000u); }
; #define PEER_SWAP() do { _Pragma("unroll") for (int q_ = 0; q_ < 8; ++q_) _Pragma("unroll") for (int c_ = 0; c_ < 4; ++c_) { \
;             const auto r_ = __builtin_amdgcn_permlane32_swap(ra[q_][c_], rb[q_][c_], false, false); ucur[q_][c_] = r_[0]; vcur[q_][c_] = r_[1]; } } while (0)
; #define PEER_LOADREC_MEM(ep_) do { \
;         _Pragma("unroll") for (int q_ = 0; q_ < 8; ++q_) { \
;             const int ia_ = __builtin_amdgcn_readfirstlane((ep_)[2 * q_]), ib_ = __builtin_amdgcn_readfirstlane((ep_)[2 * q_ + 1]); \
;             ra[q_] = *(const u32x4*)(REC + (size_t)ia_ * 1024); rb[q_] = *(const u32x4*)(REC + (size_t)ib_ * 1024); } } while (0)
; #define PEER_NEXTOPS(t_) do { const u32x4* xr_ = (const u32x4*)(xb + (size_t)(t_) * PA + 32 * l5); xq[0] = xr_[0]; xq[1] = xr_[1]; xq[2] = xr_[2]; xq[3] = xr_[3]; \
;         ivq0 = eidx[(size_t)(t_) * 128 + lane]; ivq1 = eidx[(size_t)(t_) * 128 + 64 + lane]; gvq0 = gate[(size_t)(t_) * 128 + lane]; gvq1 = gate[(size_t)(t_) * 128 + 64 + lane]; } while (0)
; DI void peer_phase(const Params& p, int layer, bool dry) {
;     ...
;     if (gw < T_TOK) {
;         PEER_LOADREC_MEM(eidx + (size_t)gw * 128);
;         PEER_SWAP();
;     }
;     u32x4 xq[4]; int ivq0 = 0, ivq1 = 0; float gvq0 = 0.f, gvq1 = 0.f;
;     ...
;     if (gw < T_TOK) PEER_NEXTOPS(gw);
;     for (int t = gw; t < T_TOK; t += nw) {
;         const int tn = (t + nw < T_TOK) ? t + nw : t;
;         const int iv0 = ivq0, iv1 = ivq1;
;         const float gv0 = gvq0, gv1 = gvq1;
;         f32x2 x2[16], f2[16];
;         {
; #pragma unroll
;             for (int j = 0; j < 4; ++j) { const u32x4 xa = xq[j];
;                 x2[4 * j] = (f32x2){bflo(xa.x), bfhi(xa.x)}; x2[4 * j + 1] = (f32x2){bflo(xa.y), bfhi(xa.y)}; x2[4 * j + 2] = (f32x2){bflo(xa.z), bfhi(xa.z)}; x2[4 * j + 3] = (f32x2){bflo(xa.w), bfhi(xa.w)}; }
;         }
; #pragma unroll
;         for (int i = 0; i < 16; ++i) f2[i] = (f32x2){0.f, 0.f};
	ds_read_b128 v[60:63], v196
	ds_read_b128 v[28:31], v233 offset:512
	ds_read_b128 v[56:59], v196 offset:64
	ds_read_b128 v[24:27], v233 offset:2592
	ds_read_b128 v[52:55], v196 offset:128
	ds_read_b128 v[20:23], v233 offset:4672
	ds_read_b128 v[48:51], v196 offset:192
	ds_read_b128 v[16:19], v233 offset:6752
	ds_read_b128 v[44:47], v196 offset:256
	ds_read_b128 v[12:15], v233 offset:8832
	ds_read_b128 v[40:43], v196 offset:320
	ds_read_b128 v[8:11], v233 offset:10912
	ds_read_b128 v[36:39], v196 offset:384
	ds_read_b128 v[4:7], v233 offset:12992
	ds_read_b128 v[32:35], v196 offset:448
	ds_read_b128 v[0:3], v233 offset:15072
	s_waitcnt lgkmcnt(0)
	global_load_dwordx4 v[234:237], v[102:103], off
	global_load_dwordx4 v[238:241], v[102:103], off offset:16
	global_load_dwordx4 v[242:245], v[102:103], off offset:32
	global_load_dwordx4 v[246:249], v[102:103], off offset:48
	global_load_dwordx4 v[130:133], v[104:105], off
	global_load_dwordx4 v[134:137], v[104:105], off offset:16
	global_load_dwordx4 v[138:141], v[104:105], off offset:32
	global_load_dwordx4 v[206:209], v[104:105], off offset:48
	s_branch .LBB0_34
.LBB0_33:
	v_mov_b32_e32 v225, v98
	v_mov_b32_e32 v227, v99
	s_andn2_b64 vcc, exec, s[18:19]
	s_cbranch_vccz .LBB0_50
.LBB0_34:
	s_mov_b32 s20, s10
	s_add_i32 s10, s10, s90
	s_cmpk_gt_i32 s10, 0x7fff
	s_cselect_b64 s[18:19], -1, 0
	s_cmp_lt_i32 s10, 0x8000
	s_cselect_b32 s22, s10, s20
	s_ashr_i32 s23, s22, 31
	s_lshl_b64 s[0:1], s[22:23], 9
	s_add_u32 s24, s92, s0
	v_mov_b32_e32 v160, 0
	s_barrier
	s_waitcnt vmcnt(4)
	v_readlane_b32 s44, v250, 42
	v_and_b32_e32 v80, 31, v96
	v_lshlrev_b32_e32 v80, 6, v80
	v_add_u32_e32 v80, s44, v80
	ds_write_b128 v80, v[76:79]
	ds_write_b128 v80, v[68:71] offset:16
	ds_write_b128 v80, v[72:75] offset:32
	ds_write_b128 v80, v[64:67] offset:48
	v_lshlrev_b32_e32 v112, 16, v76
	v_and_b32_e32 v113, 0xffff0000, v76
	v_lshlrev_b32_e32 v114, 16, v72
	v_and_b32_e32 v115, 0xffff0000, v72
	v_lshlrev_b32_e32 v116, 16, v77
	v_and_b32_e32 v117, 0xffff0000, v77
	v_lshlrev_b32_e32 v118, 16, v73
	v_and_b32_e32 v119, 0xffff0000, v73
	v_lshlrev_b32_e32 v120, 16, v78
	v_and_b32_e32 v121, 0xffff0000, v78
	v_lshlrev_b32_e32 v122, 16, v74
	v_and_b32_e32 v123, 0xffff0000, v74
	v_lshlrev_b32_e32 v124, 16, v79
	v_and_b32_e32 v125, 0xffff0000, v79
	v_lshlrev_b32_e32 v126, 16, v75
	v_and_b32_e32 v127, 0xffff0000, v75
	v_lshlrev_b32_e32 v142, 16, v68
	v_and_b32_e32 v143, 0xffff0000, v68
	v_lshlrev_b32_e32 v144, 16, v64
	v_and_b32_e32 v145, 0xffff0000, v64
	v_lshlrev_b32_e32 v146, 16, v69
	v_and_b32_e32 v147, 0xffff0000, v69
	v_lshlrev_b32_e32 v148, 16, v65
	v_and_b32_e32 v149, 0xffff0000, v65
	v_lshlrev_b32_e32 v150, 16, v70
	v_and_b32_e32 v151, 0xffff0000, v70
	v_lshlrev_b32_e32 v152, 16, v66
	v_and_b32_e32 v153, 0xffff0000, v66
	v_lshlrev_b32_e32 v154, 16, v71
	v_and_b32_e32 v155, 0xffff0000, v71
	v_lshlrev_b32_e32 v156, 16, v67
	v_and_b32_e32 v157, 0xffff0000, v67
	s_addc_u32 s25, s93, s1
	s_mov_b32 s21, 0
	s_mov_b32 s11, 0
	v_mov_b32_e32 v161, v160
	v_mov_b32_e32 v188, v160
	v_mov_b32_e32 v189, v160
	v_mov_b32_e32 v164, v160
	v_mov_b32_e32 v165, v160
	v_mov_b32_e32 v168, v160
	v_mov_b32_e32 v169, v160
	v_mov_b32_e32 v172, v160
	v_mov_b32_e32 v173, v160
	v_mov_b32_e32 v176, v160
	v_mov_b32_e32 v177, v160
	v_mov_b32_e32 v180, v160
	v_mov_b32_e32 v181, v160
	v_mov_b32_e32 v184, v160
	v_mov_b32_e32 v185, v160
	v_mov_b32_e32 v186, v160
	v_mov_b32_e32 v187, v160
	v_mov_b32_e32 v158, v160
	v_mov_b32_e32 v159, v160
	v_mov_b32_e32 v162, v160
	v_mov_b32_e32 v163, v160
	v_mov_b32_e32 v166, v160
	v_mov_b32_e32 v167, v160
	v_mov_b32_e32 v170, v160
	v_mov_b32_e32 v171, v160
	v_mov_b32_e32 v174, v160
	v_mov_b32_e32 v175, v160
	v_mov_b32_e32 v178, v160
	v_mov_b32_e32 v179, v160
	v_mov_b32_e32 v182, v160
	v_mov_b32_e32 v183, v160
	s_branch .LBB0_36

; #define PEER_LOADREC_FROM(isrc_, lb_) do { \
;         _Pragma("unroll") for (int q_ = 0; q_ < 8; ++q_) { \
;             const int ia_ = __builtin_amdgcn_readlane(isrc_, (lb_) + 2 * q_), ib_ = __builtin_amdgcn_readlane(isrc_, (lb_) + 2 * q_ + 1); \
;             ra[q_] = *(const u32x4*)(REC + (size_t)ia_ * 1024); rb[q_] = *(const u32x4*)(REC + (size_t)ib_ * 1024); } } while (0)
; #define PEER_SWAP() do { _Pragma("unroll") for (int q_ = 0; q_ < 8; ++q_) _Pragma("unroll") for (int c_ = 0; c_ < 4; ++c_) { \
;             const auto r_ = __builtin_amdgcn_permlane32_swap(ra[q_][c_], rb[q_][c_], false, false); ucur[q_][c_] = r_[0]; vcur[q_][c_] = r_[1]; } } while (0)
; #define PEER_LOADREC_MEM(ep_) do { \
;         _Pragma("unroll") for (int q_ = 0; q_ < 8; ++q_) { \
;             const int ia_ = __builtin_amdgcn_readfirstlane((ep_)[2 * q_]), ib_ = __builtin_amdgcn_readfirstlane((ep_)[2 * q_ + 1]); \
;             ra[q_] = *(const u32x4*)(REC + (size_t)ia_ * 1024); rb[q_] = *(const u32x4*)(REC + (size_t)ib_ * 1024); } } while (0)
; DI void peer_phase(const Params& p, int layer, bool dry) {
;     ...
;     if (gw < T_TOK) {
;         PEER_LOADREC_MEM(eidx + (size_t)gw * 128);
;         PEER_SWAP();
;     }
;     u32x4 xq[4]; int ivq0 = 0, ivq1 = 0; float gvq0 = 0.f, gvq1 = 0.f;
;     ...
;         for (int bt = 0; bt < 8; ++bt) {
;             if (bt < 7) { const int nb = bt + 1; const int isrc = (nb < 4) ? iv0 : iv1; const int lb = (nb & 3) * 16; PEER_LOADREC_FROM(isrc, lb); }
;             else PEER_LOADREC_MEM(eidx + (size_t)tn * 128);
;             const int myidx = __shfl((bt < 4) ? iv0 : iv1, (bt & 3) * 16 + esel16);
;             const float gsc = __shfl((bt < 4) ? gv0 : gv1, (bt & 3) * 16 + esel16) * SV[myidx], usc = SU[myidx];
.LBB0_38:
	s_andn2_b64 vcc, exec, s[72:73]
	s_cbranch_vccnz .LBB0_35
	v_lshlrev_b32_e32 v70, 2, v96
	s_add_u32 s40, s76, s0
	s_addc_u32 s41, s77, s1
	global_load_dword v218, v70, s[24:25]
	global_load_dword v98, v70, s[24:25] offset:256
	global_load_dword v226, v70, s[40:41]
	global_load_dword v99, v70, s[40:41] offset:256
	s_mov_b32 s60, 48
	s_movk_i32 s21, 0x80
	s_waitcnt vmcnt(0)
	v_lshrrev_b32_e32 v64, 11, v218
	v_lshrrev_b32_e32 v65, 11, v98
	s_mov_b32 s36, 0
	v_cmp_eq_u32_e64 s[28:29], 0, v64
	v_cmp_eq_u32_e64 s[30:31], 0, v65
	s_bcnt1_i32_b64 s34, s[28:29]
	s_bcnt1_i32_b64 s35, s[30:31]
	v_mbcnt_lo_u32_b32 v68, s28, 0
	v_mbcnt_hi_u32_b32 v68, s29, v68
	v_mbcnt_lo_u32_b32 v69, s30, 0
	v_mbcnt_hi_u32_b32 v69, s31, v69
	v_add_u32_e32 v68, s36, v68
	s_add_i32 s36, s36, s34
	v_add_u32_e32 v69, s36, v69
	s_add_i32 s36, s36, s35
	v_cndmask_b32_e64 v66, v66, v68, s[28:29]
	v_cndmask_b32_e64 v67, v67, v69, s[30:31]
	v_cmp_eq_u32_e64 s[28:29], 1, v64
	v_cmp_eq_u32_e64 s[30:31], 1, v65
	s_bcnt1_i32_b64 s34, s[28:29]
	s_bcnt1_i32_b64 s35, s[30:31]
	v_mbcnt_lo_u32_b32 v68, s28, 0
	v_mbcnt_hi_u32_b32 v68, s29, v68
	v_mbcnt_lo_u32_b32 v69, s30, 0
	v_mbcnt_hi_u32_b32 v69, s31, v69
	v_add_u32_e32 v68, s36, v68
	s_add_i32 s36, s36, s34
	v_add_u32_e32 v69, s36, v69
	s_add_i32 s36, s36, s35
	v_cndmask_b32_e64 v66, v66, v68, s[28:29]
	v_cndmask_b32_e64 v67, v67, v69, s[30:31]
	v_cmp_eq_u32_e64 s[28:29], 2, v64
	v_cmp_eq_u32_e64 s[30:31], 2, v65
	s_bcnt1_i32_b64 s34, s[28:29]
	s_bcnt1_i32_b64 s35, s[30:31]
	v_mbcnt_lo_u32_b32 v68, s28, 0
	v_mbcnt_hi_u32_b32 v68, s29, v68
	v_mbcnt_lo_u32_b32 v69, s30, 0
	v_mbcnt_hi_u32_b32 v69, s31, v69
	v_add_u32_e32 v68, s36, v68
	s_add_i32 s36, s36, s34
	v_add_u32_e32 v69, s36, v69
	s_add_i32 s36, s36, s35
	v_cndmask_b32_e64 v66, v66, v68, s[28:29]
	v_cndmask_b32_e64 v67, v67, v69, s[30:31]
	v_cmp_eq_u32_e64 s[28:29], 3, v64
	v_cmp_eq_u32_e64 s[30:31], 3, v65
	s_bcnt1_i32_b64 s34, s[28:29]
	s_bcnt1_i32_b64 s35, s[30:31]
	v_mbcnt_lo_u32_b32 v68, s28, 0
	v_mbcnt_hi_u32_b32 v68, s29, v68
	v_mbcnt_lo_u32_b32 v69, s30, 0
	v_mbcnt_hi_u32_b32 v69, s31, v69
	v_add_u32_e32 v68, s36, v68
	s_add_i32 s36, s36, s34
	v_add_u32_e32 v69, s36, v69
	s_add_i32 s36, s36, s35
	v_cndmask_b32_e64 v66, v66, v68, s[28:29]
	v_cndmask_b32_e64 v67, v67, v69, s[30:31]
	v_cmp_eq_u32_e64 s[28:29], 4, v64
	v_cmp_eq_u32_e64 s[30:31], 4, v65
	s_bcnt1_i32_b64 s34, s[28:29]
	s_bcnt1_i32_b64 s35, s[30:31]
	v_mbcnt_lo_u32_b32 v68, s28, 0
	v_mbcnt_hi_u32_b32 v68, s29, v68
	v_mbcnt_lo_u32_b32 v69, s30, 0
	v_mbcnt_hi_u32_b32 v69, s31, v69
	v_add_u32_e32 v68, s36, v68
	s_add_i32 s36, s36, s34
	v_add_u32_e32 v69, s36, v69
	s_add_i32 s36, s36, s35
	v_cndmask_b32_e64 v66, v66, v68, s[28:29]
	v_cndmask_b32_e64 v67, v67, v69, s[30:31]
	v_cmp_eq_u32_e64 s[28:29], 5, v64
	v_cmp_eq_u32_e64 s[30:31], 5, v65
	s_bcnt1_i32_b64 s34, s[28:29]
	s_bcnt1_i32_b64 s35, s[30:31]
	v_mbcnt_lo_u32_b32 v68, s28, 0
	v_mbcnt_hi_u32_b32 v68, s29, v68
	v_mbcnt_lo_u32_b32 v69, s30, 0
	v_mbcnt_hi_u32_b32 v69, s31, v69
	v_add_u32_e32 v68, s36, v68
	s_add_i32 s36, s36, s34
	v_add_u32_e32 v69, s36, v69
	s_add_i32 s36, s36, s35
	v_cndmask_b32_e64 v66, v66, v68, s[28:29]
	v_cndmask_b32_e64 v67, v67, v69, s[30:31]
	v_cmp_eq_u32_e64 s[28:29], 6, v64
	v_cmp_eq_u32_e64 s[30:31], 6, v65
	s_bcnt1_i32_b64 s34, s[28:29]
	s_bcnt1_i32_b64 s35, s[30:31]
	v_mbcnt_lo_u32_b32 v68, s28, 0
	v_mbcnt_hi_u32_b32 v68, s29, v68
	v_mbcnt_lo_u32_b32 v69, s30, 0
	v_mbcnt_hi_u32_b32 v69, s31, v69
	v_add_u32_e32 v68, s36, v68
	s_add_i32 s36, s36, s34
	v_add_u32_e32 v69, s36, v69
	s_add_i32 s36, s36, s35
	v_cndmask_b32_e64 v66, v66, v68, s[28:29]
	v_cndmask_b32_e64 v67, v67, v69, s[30:31]
	v_cmp_eq_u32_e64 s[28:29], 7, v64
	v_cmp_eq_u32_e64 s[30:31], 7, v65
	s_bcnt1_i32_b64 s34, s[28:29]
	s_bcnt1_i32_b64 s35, s[30:31]
	v_mbcnt_lo_u32_b32 v68, s28, 0
	v_mbcnt_hi_u32_b32 v68, s29, v68
	v_mbcnt_lo_u32_b32 v69, s30, 0
	v_mbcnt_hi_u32_b32 v69, s31, v69
	v_add_u32_e32 v68, s36, v68
	s_add_i32 s36, s36, s34
	v_add_u32_e32 v69, s36, v69
	s_add_i32 s36, s36, s35
	v_cndmask_b32_e64 v66, v66, v68, s[28:29]
	v_cndmask_b32_e64 v67, v67, v69, s[30:31]
	v_lshl_add_u32 v71, v66, 2, s32
	v_lshl_add_u32 v72, v67, 2, s32
	v_lshl_add_u32 v70, v96, 2, s32
	ds_write_b32 v71, v218
	ds_write_b32 v72, v98
	ds_write_b32 v71, v226 offset:512
	ds_write_b32 v72, v99 offset:512
	s_waitcnt lgkmcnt(0)
	ds_read_b32 v218, v70
	ds_read_b32 v98, v70 offset:256
	ds_read_b32 v226, v70 offset:512
	ds_read_b32 v99, v70 offset:768
	s_waitcnt lgkmcnt(0)
	v_readlane_b32 s28, v218, 0
	v_readlane_b32 s26, v218, 1
	v_readlane_b32 s30, v218, 2
	v_readlane_b32 s40, v218, 3
	v_readlane_b32 s34, v218, 4
	v_readlane_b32 s38, v218, 5
	v_readlane_b32 s50, v218, 6
	v_readlane_b32 s48, v218, 7
	v_readlane_b32 s54, v218, 8
	v_readlane_b32 s46, v218, 9
	v_readlane_b32 s58, v218, 10
	v_readlane_b32 s36, v218, 11
	v_readlane_b32 s62, v218, 12
	v_readlane_b32 s52, v218, 13
	v_readlane_b32 s64, v218, 14
	v_readlane_b32 s56, v218, 15
	s_branch .LBB0_35
; #define PEER_NEXTOPS(t_) do { const u32x4* xr_ = (const u32x4*)(xb + (size_t)(t_) * PA + 32 * l5); xq[0] = xr_[0]; xq[1] = xr_[1]; xq[2] = xr_[2]; xq[3] = xr_[3]; \
;         ivq0 = eidx[(size_t)(t_) * 128 + lane]; ivq1 = eidx[(size_t)(t_) * 128 + 64 + lane]; gvq0 = gate[(size_t)(t_) * 128 + lane]; gvq1 = gate[(size_t)(t_) * 128 + 64 + lane]; } while (0)
; DI void peer_phase(const Params& p, int layer, bool dry) {
;     ...
;         float fh[16];
; #pragma unroll
;         for (int i = 0; i < 8; ++i) {
;             const float s0 = f2[i].x + __shfl_xor(f2[i].x, 32), s1 = f2[i].y + __shfl_xor(f2[i].y, 32);
;             const float s2 = f2[8 + i].x + __shfl_xor(f2[8 + i].x, 32), s3 = f2[8 + i].y + __shfl_xor(f2[8 + i].y, 32);
;             fh[2 * i] = hi ? s2 : s0; fh[2 * i + 1] = hi ? s3 : s1;
;         }
;         const int cb = 32 * l5 + 16 * hi;
;         float hv[16]; float s = 0.f;
; #pragma unroll
;         for (int i = 0; i < 8; ++i) {
;             const float xa = hi ? x2[8 + i].x : x2[i].x, xc = hi ? x2[8 + i].y : x2[i].y;
;             hv[2 * i] = ALPHA * xa + fh[2 * i]; hv[2 * i + 1] = ALPHA * xc + fh[2 * i + 1];
;             s += hv[2 * i] + hv[2 * i + 1];
;         }
;         PEER_NEXTOPS(tn);
;         const float mean = wave_sum(s) * (1.f / DM); float qv = 0.f;
.LBB0_40:
	ds_bpermute_b32 v64, v215, v188
	ds_bpermute_b32 v65, v215, v189
	ds_bpermute_b32 v66, v215, v158
	ds_bpermute_b32 v67, v215, v159
	ds_bpermute_b32 v88, v215, v184
	ds_bpermute_b32 v89, v215, v185
	ds_bpermute_b32 v90, v215, v182
	ds_bpermute_b32 v91, v215, v183
	ds_bpermute_b32 v92, v215, v186
	ds_bpermute_b32 v93, v215, v187
	ds_bpermute_b32 v94, v215, v160
	ds_bpermute_b32 v95, v215, v161
	ds_bpermute_b32 v68, v215, v164
	ds_bpermute_b32 v69, v215, v165
	ds_bpermute_b32 v70, v215, v162
	ds_bpermute_b32 v71, v215, v163
	ds_bpermute_b32 v72, v215, v168
	ds_bpermute_b32 v73, v215, v169
	ds_bpermute_b32 v74, v215, v166
	ds_bpermute_b32 v75, v215, v167
	ds_bpermute_b32 v84, v215, v180
	ds_bpermute_b32 v85, v215, v181
	ds_bpermute_b32 v86, v215, v178
	ds_bpermute_b32 v87, v215, v179
	ds_bpermute_b32 v76, v215, v172
	ds_bpermute_b32 v77, v215, v173
	ds_bpermute_b32 v78, v215, v170
	ds_bpermute_b32 v79, v215, v171
	ds_bpermute_b32 v80, v215, v176
	ds_bpermute_b32 v81, v215, v177
	ds_bpermute_b32 v82, v215, v174
	ds_bpermute_b32 v83, v215, v175
	s_waitcnt lgkmcnt(14)
	v_pk_add_f32 v[92:93], v[186:187], v[92:93]
	v_pk_add_f32 v[94:95], v[160:161], v[94:95]
	v_pk_add_f32 v[88:89], v[184:185], v[88:89]
	v_pk_add_f32 v[90:91], v[182:183], v[90:91]
	v_pk_add_f32 v[64:65], v[188:189], v[64:65]
	v_pk_add_f32 v[66:67], v[158:159], v[66:67]
	v_cndmask_b32_e64 v113, v115, v113, s[8:9]
	v_cndmask_b32_e64 v112, v114, v112, s[8:9]
	v_cndmask_b32_e64 v115, v119, v117, s[8:9]
	v_cndmask_b32_e64 v114, v118, v116, s[8:9]
	v_cndmask_b32_e64 v119, v127, v125, s[8:9]
	v_cndmask_b32_e64 v118, v126, v124, s[8:9]
	v_cndmask_b32_e64 v125, v153, v151, s[8:9]
	v_cndmask_b32_e64 v124, v152, v150, s[8:9]
	v_cndmask_b32_e64 v127, v157, v155, s[8:9]
	v_cndmask_b32_e64 v126, v156, v154, s[8:9]
	v_cndmask_b32_e64 v93, v95, v93, s[8:9]
	v_cndmask_b32_e64 v92, v94, v92, s[8:9]
	v_cndmask_b32_e64 v89, v91, v89, s[8:9]
	v_cndmask_b32_e64 v88, v90, v88, s[8:9]
	v_pk_add_f32 v[68:69], v[164:165], v[68:69]
	v_pk_add_f32 v[70:71], v[162:163], v[70:71]
	v_cndmask_b32_e64 v65, v67, v65, s[8:9]
	v_cndmask_b32_e64 v64, v66, v64, s[8:9]
	v_pk_fma_f32 v[94:95], v[126:127], s[78:79], v[92:93] op_sel_hi:[1,0,1]
	v_pk_fma_f32 v[92:93], v[124:125], s[78:79], v[88:89] op_sel_hi:[1,0,1]
	s_waitcnt lgkmcnt(10)
	v_pk_add_f32 v[84:85], v[180:181], v[84:85]
	s_waitcnt lgkmcnt(8)
	v_pk_add_f32 v[86:87], v[178:179], v[86:87]
	v_pk_add_f32 v[72:73], v[168:169], v[72:73]
	v_pk_add_f32 v[74:75], v[166:167], v[74:75]
	v_cndmask_b32_e64 v69, v71, v69, s[8:9]
	v_cndmask_b32_e64 v68, v70, v68, s[8:9]
	v_pk_fma_f32 v[112:113], v[112:113], s[78:79], v[64:65] op_sel_hi:[1,0,1]
	v_cndmask_b32_e64 v117, v123, v121, s[8:9]
	v_cndmask_b32_e64 v116, v122, v120, s[8:9]
	v_cndmask_b32_e64 v123, v149, v147, s[8:9]
	v_cndmask_b32_e64 v122, v148, v146, s[8:9]
	v_mov_b32_e32 v88, v92
	v_mov_b32_e32 v89, v94
	v_mov_b32_e32 v90, v93
	v_mov_b32_e32 v91, v95
	v_cndmask_b32_e64 v85, v87, v85, s[8:9]
	v_cndmask_b32_e64 v84, v86, v84, s[8:9]
	s_waitcnt lgkmcnt(2)
	v_pk_add_f32 v[80:81], v[176:177], v[80:81]
	s_waitcnt lgkmcnt(0)
	v_pk_add_f32 v[82:83], v[174:175], v[82:83]
	v_pk_add_f32 v[76:77], v[172:173], v[76:77]
	v_pk_add_f32 v[78:79], v[170:171], v[78:79]
	v_cndmask_b32_e64 v73, v75, v73, s[8:9]
	v_cndmask_b32_e64 v72, v74, v72, s[8:9]
	v_pk_fma_f32 v[114:115], v[114:115], s[78:79], v[68:69] op_sel_hi:[1,0,1]
	v_add_f32_e32 v64, v112, v113
	v_cndmask_b32_e64 v121, v145, v143, s[8:9]
	v_cndmask_b32_e64 v120, v144, v142, s[8:9]
	v_pk_add_f32 v[88:89], v[88:89], v[90:91]
	v_pk_fma_f32 v[90:91], v[122:123], s[78:79], v[84:85] op_sel_hi:[1,0,1]
	v_cndmask_b32_e64 v81, v83, v81, s[8:9]
	v_cndmask_b32_e64 v80, v82, v80, s[8:9]
	v_cndmask_b32_e64 v77, v79, v77, s[8:9]
	v_cndmask_b32_e64 v76, v78, v76, s[8:9]
	v_pk_fma_f32 v[84:85], v[116:117], s[78:79], v[72:73] op_sel_hi:[1,0,1]
	v_add_f32_e32 v68, v114, v115
	v_add_f32_e32 v64, 0, v64
	v_pk_fma_f32 v[120:121], v[120:121], s[78:79], v[80:81] op_sel_hi:[1,0,1]
	v_pk_fma_f32 v[86:87], v[118:119], s[78:79], v[76:77] op_sel_hi:[1,0,1]
	v_add_f32_e32 v72, v84, v85
	v_add_f32_e32 v64, v64, v68
	v_mov_b32_e32 v80, v120
	v_mov_b32_e32 v81, v90
	v_mov_b32_e32 v82, v121
	v_mov_b32_e32 v83, v91
	v_add_f32_e32 v76, v86, v87
	v_add_f32_e32 v64, v64, v72
	v_pk_add_f32 v[80:81], v[80:81], v[82:83]
	v_add_f32_e32 v64, v64, v76
	v_add_f32_e32 v64, v64, v80
	v_add_f32_e32 v64, v64, v81
	v_add_f32_e32 v64, v64, v88
	v_add_f32_e32 v64, v64, v89
	ds_bpermute_b32 v65, v214, v64
	s_lshl_b64 s[22:23], s[22:23], 11
	v_lshl_add_u64 v[76:77], v[100:101], 0, s[22:23]
	s_ashr_i32 s21, s20, 31
	s_waitcnt lgkmcnt(0)
; DI unsigned pk2(float lo, float hi) { const f32x2 v = {lo, hi}; return __builtin_bit_cast(unsigned, __builtin_convertvector(v, bf16x2_t)); }
; #define PEER_NEXTOPS(t_) do { const u32x4* xr_ = (const u32x4*)(xb + (size_t)(t_) * PA + 32 * l5); xq[0] = xr_[0]; xq[1] = xr_[1]; xq[2] = xr_[2]; xq[3] = xr_[3]; \
;         ivq0 = eidx[(size_t)(t_) * 128 + lane]; ivq1 = eidx[(size_t)(t_) * 128 + 64 + lane]; gvq0 = gate[(size_t)(t_) * 128 + lane]; gvq1 = gate[(size_t)(t_) * 128 + 64 + lane]; } while (0)
; DI void peer_phase(const Params& p, int layer, bool dry) {
;     ...
;         PEER_NEXTOPS(tn);
;         const float mean = wave_sum(s) * (1.f / DM); float qv = 0.f;
; #pragma unroll
;         for (int i = 0; i < 16; ++i) { hv[i] -= mean; qv += hv[i] * hv[i]; }
;         const float rstd = rsqrtf(wave_sum(qv) * (1.f / DM) + LN_EPS);
;         float* orow = p.out + (size_t)t * DM + cb;
;         float ov[16];
; #pragma unroll
;         for (int c = 0; c < 4; ++c) {
;             const f32x4 gg = *(const f32x4*)(g2 + cb + 4 * c), bb = *(const f32x4*)(b2 + cb + 4 * c);
;             f32x4 o; o.x = hv[4 * c] * rstd * gg.x + bb.x; o.y = hv[4 * c + 1] * rstd * gg.y + bb.y; o.z = hv[4 * c + 2] * rstd * gg.z + bb.z; o.w = hv[4 * c + 3] * rstd * gg.w + bb.w;
;             if (!dry && layer == 1) *(f32x4*)(orow + 4 * c) = o;
;             ov[4 * c] = o.x; ov[4 * c + 1] = o.y; ov[4 * c + 2] = o.z; ov[4 * c + 3] = o.w;
;         }
;         u32x4 w0, w1;
;         w0.x = pk2(ov[0], ov[1]); w0.y = pk2(ov[2], ov[3]); w0.z = pk2(ov[4], ov[5]); w0.w = pk2(ov[6], ov[7]);
;         w1.x = pk2(ov[8], ov[9]); w1.y = pk2(ov[10], ov[11]); w1.z = pk2(ov[12], ov[13]); w1.w = pk2(ov[14], ov[15]);
;         u32x4* xw = (u32x4*)(xb + (size_t)t * PA + cb);
;         if (!dry) { xw[0] = w0; xw[1] = w1;
;             if (layer == 0) { u32x4* xr2 = (u32x4*)((bf16_t*)(ws + OFF_R3) + (size_t)t * DM + cb); xr2[0] = w0; xr2[1] = w1; } }
	v_add_f32_e32 v64, v64, v65
	ds_bpermute_b32 v65, v213, v64
	s_waitcnt lgkmcnt(0)
	v_add_f32_e32 v80, v64, v65
	ds_bpermute_b32 v81, v212, v80
	global_load_dwordx4 v[64:67], v[76:77], off offset:48
	global_load_dwordx4 v[72:75], v[76:77], off offset:32
	global_load_dwordx4 v[68:71], v[76:77], off offset:16
	s_nop 0
	global_load_dwordx4 v[76:79], v[76:77], off
	s_waitcnt lgkmcnt(0)
	v_add_f32_e32 v89, v80, v81
	ds_bpermute_b32 v116, v211, v89
	s_waitcnt lgkmcnt(0)
	v_add_f32_e32 v118, v89, v116
	ds_bpermute_b32 v119, v97, v118
	s_waitcnt lgkmcnt(0)
	v_add_f32_e32 v122, v118, v119
	ds_bpermute_b32 v123, v215, v122
	s_lshl_b64 s[0:1], s[20:21], 12
	s_waitcnt lgkmcnt(0)
	v_add_f32_e32 v88, v122, v123
	v_mul_f32_e32 v122, 0x3a800000, v88
	v_pk_add_f32 v[124:125], v[112:113], v[122:123] op_sel_hi:[1,0] neg_lo:[0,1] neg_hi:[0,1]
	v_pk_add_f32 v[126:127], v[114:115], v[122:123] op_sel_hi:[1,0] neg_lo:[0,1] neg_hi:[0,1]
	v_pk_mul_f32 v[112:113], v[124:125], v[124:125]
	v_pk_mul_f32 v[114:115], v[126:127], v[126:127]
	v_add_f32_e32 v112, v112, v113
	v_pk_add_f32 v[84:85], v[84:85], v[122:123] op_sel_hi:[1,0] neg_lo:[0,1] neg_hi:[0,1]
	v_add_f32_e32 v112, v114, v112
	v_pk_mul_f32 v[142:143], v[84:85], v[84:85]
	v_add_f32_e32 v112, v115, v112
	v_pk_add_f32 v[86:87], v[86:87], v[122:123] op_sel_hi:[1,0] neg_lo:[0,1] neg_hi:[0,1]
	v_add_f32_e32 v112, v142, v112
	v_pk_mul_f32 v[144:145], v[86:87], v[86:87]
	v_add_f32_e32 v112, v143, v112
	v_pk_add_f32 v[88:89], v[120:121], v[122:123] op_sel_hi:[1,0] neg_lo:[0,1] neg_hi:[0,1]
	v_add_f32_e32 v112, v144, v112
	v_pk_mul_f32 v[120:121], v[88:89], v[88:89]
	v_add_f32_e32 v112, v145, v112
	v_pk_add_f32 v[90:91], v[90:91], v[122:123] op_sel_hi:[1,0] neg_lo:[0,1] neg_hi:[0,1]
	v_add_f32_e32 v112, v120, v112
	v_pk_mul_f32 v[146:147], v[90:91], v[90:91]
	v_add_f32_e32 v112, v121, v112
	v_pk_add_f32 v[92:93], v[92:93], v[122:123] op_sel_hi:[1,0] neg_lo:[0,1] neg_hi:[0,1]
	v_add_f32_e32 v112, v146, v112
	v_pk_mul_f32 v[148:149], v[92:93], v[92:93]
	v_add_f32_e32 v112, v147, v112
	v_pk_add_f32 v[94:95], v[94:95], v[122:123] op_sel_hi:[1,0] neg_lo:[0,1] neg_hi:[0,1]
	v_add_f32_e32 v112, v148, v112
	v_pk_mul_f32 v[122:123], v[94:95], v[94:95]
	v_add_f32_e32 v112, v149, v112
	v_add_f32_e32 v112, v122, v112
	v_add_f32_e32 v112, v123, v112
	ds_bpermute_b32 v113, v214, v112
	s_waitcnt lgkmcnt(0)
	v_add_f32_e32 v112, v112, v113
	ds_bpermute_b32 v113, v213, v112
	s_waitcnt lgkmcnt(0)
	v_add_f32_e32 v112, v112, v113
	ds_bpermute_b32 v113, v212, v112
	s_waitcnt lgkmcnt(0)
	v_add_f32_e32 v112, v112, v113
	ds_bpermute_b32 v113, v211, v112
	s_waitcnt lgkmcnt(0)
	v_add_f32_e32 v112, v112, v113
	ds_bpermute_b32 v113, v97, v112
	s_waitcnt lgkmcnt(0)
	v_add_f32_e32 v112, v112, v113
	ds_bpermute_b32 v113, v215, v112
	s_waitcnt lgkmcnt(0)
	v_add_f32_e32 v112, v112, v113
	v_fmamk_f32 v112, v112, 0x3a800000, v195
	v_mul_f32_e32 v113, 0x4b800000, v112
	v_cmp_gt_f32_e32 vcc, s69, v112
	s_nop 1
	v_cndmask_b32_e32 v112, v112, v113, vcc
	v_rsq_f32_e32 v114, v112
	v_lshl_add_u64 v[112:113], v[110:111], 0, s[0:1]
	v_mul_f32_e32 v115, 0x45800000, v114
	v_cndmask_b32_e32 v114, v114, v115, vcc
	v_pk_mul_f32 v[120:121], v[124:125], v[114:115] op_sel_hi:[1,0]
	s_and_b64 vcc, exec, s[16:17]
	v_pk_fma_f32 v[80:81], v[234:235], v[120:121], v[130:131]
	v_pk_mul_f32 v[116:117], v[126:127], v[114:115] op_sel_hi:[1,0]
	s_nop 0
	v_pk_fma_f32 v[82:83], v[236:237], v[116:117], v[132:133]
	s_cbranch_vccz .LBB0_42
	global_store_dwordx4 v[112:113], v[80:83], off
